# GLA main loop: exact vmcnt ladders before the LDS stores keep the next chunk's prefetch group in flight; per-chunk vector load issued by every wave
# speedup vs baseline: 1.0068x; 1.0068x over previous
.LBB0_348:
	s_cmp_lt_u32 s72, 30
	s_cselect_b64 s[54:55], -1, 0
	s_cmp_gt_u32 s72, 29
	s_cselect_b64 s[34:35], -1, 0
	s_and_b64 vcc, exec, s[34:35]
	v_add_u32_e32 v177, s71, v118
	v_add_u32_e32 v95, s71, v119
	s_cbranch_vccnz .LBB0_352
	v_add_u32_e32 v28, 0x80, v177
	v_mad_i64_i32 v[32:33], s[56:57], v28, s73, v[86:87]
	s_add_i32 s56, s30, -4
	s_ashr_i32 s57, s56, 31
	s_lshl_b64 s[56:57], s[56:57], 14
	v_lshl_add_u64 v[36:37], v[88:89], 0, s[56:57]
	v_mov_b32_e32 v81, v85
	v_lshl_add_u64 v[44:45], v[36:37], 0, v[80:81]
	v_add_u32_e32 v36, 0xa0, v177
	v_add_co_u32_e32 v48, vcc, 0x2000, v44
	v_add_u32_e32 v52, 0x80, v95
	v_mad_i64_i32 v[46:47], s[56:57], v36, s73, v[86:87]
	v_addc_co_u32_e32 v49, vcc, 0, v45, vcc
	v_mad_i64_i32 v[52:53], s[56:57], v52, s73, v[92:93]
	global_load_dwordx4 v[28:31], v[32:33], off
	s_nop 0
	global_load_dwordx4 v[32:35], v[32:33], off offset:1024
	s_nop 0
	global_load_dwordx4 v[40:43], v[44:45], off
	global_load_dwordx4 v[36:39], v[46:47], off
	s_nop 0
	global_load_dwordx4 v[44:47], v[46:47], off offset:1024
	s_nop 0
	global_load_dwordx4 v[48:51], v[48:49], off
	v_mov_b32_e32 v172, 0
	global_load_dwordx4 v[52:55], v[52:53], off offset:2048
	v_add_u32_e32 v56, -3, v94
	v_ashrrev_i32_e32 v57, 31, v56
	v_lshlrev_b64 v[56:57], 11, v[56:57]
	v_lshl_add_u64 v[56:57], v[90:91], 0, v[56:57]
	global_load_dword v172, v[56:57], off
.LBB0_351:
.LBB0_352:
	ds_read_b128 v[248:251], v133
	v_add_u32_e32 v173, v134, v136
	ds_read_b128 v[196:199], v173
	v_add_u32_e32 v176, v137, v135
	ds_read_b128 v[212:215], v176 offset:16384
	v_add_u32_e32 v231, v137, v138
	ds_read_b128 v[216:219], v231 offset:16384
	v_add_u32_e32 v173, v134, v139
	ds_read_b128 v[200:203], v173
	v_add_u32_e32 v176, v140, v135
	ds_read_b128 v[220:223], v176 offset:16384
	v_add_u32_e32 v231, v140, v138
	ds_read_b128 v[224:227], v231 offset:16384
	v_add_u32_e32 v173, v134, v141
	ds_read_b128 v[204:207], v173
	v_add_u32_e32 v176, v142, v135
	ds_read_b128 v[232:235], v176 offset:16384
	v_add_u32_e32 v231, v142, v138
	ds_read_b128 v[236:239], v231 offset:16384
	v_add_u32_e32 v173, v134, v143
	ds_read_b128 v[208:211], v173
	v_add_u32_e32 v176, v144, v135
	ds_read_b128 v[240:243], v176 offset:16384
	v_add_u32_e32 v231, v144, v138
	ds_read_b128 v[244:247], v231 offset:16384
	s_waitcnt lgkmcnt(12)
	v_pk_mul_f32 v[64:65], v[112:113], v[248:249]
	v_pk_mul_f32 v[66:67], v[114:115], v[250:251]
	v_pk_mul_f32 v[68:69], v[108:109], v[248:249]
	v_pk_mul_f32 v[70:71], v[110:111], v[250:251]
	v_cvt_pk_bf16_f32 v72, v64, v65
	v_cvt_pk_bf16_f32 v73, v66, v67
	v_cvt_pk_bf16_f32 v74, v68, v69
	v_cvt_pk_bf16_f32 v75, v70, v71
	ds_write2st64_b64 v153, v[72:73], v[74:75] offset1:8
	v_pk_mul_f32 v[64:65], v[104:105], v[248:249]
	v_pk_mul_f32 v[66:67], v[106:107], v[250:251]
	v_pk_mul_f32 v[68:69], v[100:101], v[248:249]
	v_pk_mul_f32 v[70:71], v[102:103], v[250:251]
	v_cvt_pk_bf16_f32 v72, v64, v65
	v_cvt_pk_bf16_f32 v73, v66, v67
	v_cvt_pk_bf16_f32 v74, v68, v69
	v_cvt_pk_bf16_f32 v75, v70, v71
	ds_write2st64_b64 v153, v[72:73], v[74:75] offset0:16 offset1:24
	s_waitcnt lgkmcnt(12)
	v_mfma_f32_16x16x32_bf16 v[60:63], v[212:215], v[196:199], 0
	s_waitcnt lgkmcnt(11)
	v_mfma_f32_16x16x32_bf16 v[56:59], v[216:219], v[196:199], 0
	ds_read_b128 v[252:255], v162 offset:32768
	ds_read_b128 v[212:215], v163 offset:49152
	ds_read_b128 v[216:219], v164 offset:49152
	s_waitcnt lgkmcnt(12)
	v_mfma_f32_16x16x32_bf16 v[60:63], v[220:223], v[200:203], v[60:63]
	s_waitcnt lgkmcnt(11)
	v_mfma_f32_16x16x32_bf16 v[56:59], v[224:227], v[200:203], v[56:59]
	ds_read_b128 v[220:223], v165 offset:49152
	ds_read_b128 v[224:227], v166 offset:49152
	s_waitcnt lgkmcnt(11)
	v_mfma_f32_16x16x32_bf16 v[60:63], v[232:235], v[204:207], v[60:63]
	s_waitcnt lgkmcnt(10)
	v_mfma_f32_16x16x32_bf16 v[56:59], v[236:239], v[204:207], v[56:59]
	ds_read_b128 v[248:251], v167 offset:32768
	ds_read_b128 v[232:235], v168 offset:49152
	ds_read_b128 v[236:239], v169 offset:49152
	s_waitcnt lgkmcnt(11)
	v_mfma_f32_16x16x32_bf16 v[60:63], v[240:243], v[208:211], v[60:63]
	s_waitcnt lgkmcnt(10)
	v_mfma_f32_16x16x32_bf16 v[56:59], v[244:247], v[208:211], v[56:59]
	ds_read_b128 v[240:243], v170 offset:49152
	ds_read_b128 v[244:247], v171 offset:49152
	s_waitcnt lgkmcnt(8)
	v_mfma_f32_16x16x32_bf16 v[76:79], v[252:255], v[212:215], 0
	s_waitcnt lgkmcnt(7)
	v_mfma_f32_16x16x32_bf16 v[72:75], v[252:255], v[216:219], 0
	s_waitcnt lgkmcnt(6)
	v_mfma_f32_16x16x32_bf16 v[68:71], v[252:255], v[220:223], 0
	s_waitcnt lgkmcnt(5)
	v_mfma_f32_16x16x32_bf16 v[64:67], v[252:255], v[224:227], 0
	ds_read_b128 v[212:215], v157 offset:49152
	ds_read_b128 v[216:219], v158 offset:49152
	ds_read_b128 v[220:223], v160 offset:49152
	ds_read_b128 v[224:227], v161 offset:49152
	s_waitcnt lgkmcnt(7)
	v_mfma_f32_16x16x32_bf16 v[76:79], v[248:251], v[232:235], v[76:79]
	s_waitcnt lgkmcnt(6)
	v_mfma_f32_16x16x32_bf16 v[72:75], v[248:251], v[236:239], v[72:75]
	s_waitcnt lgkmcnt(5)
	v_mfma_f32_16x16x32_bf16 v[68:71], v[248:251], v[240:243], v[68:71]
	s_waitcnt lgkmcnt(4)
	v_mfma_f32_16x16x32_bf16 v[64:67], v[248:251], v[244:247], v[64:67]
	v_cndmask_b32_e64 v60, v60, 0, s[6:7]
	v_cndmask_b32_e64 v61, 0, v61, s[8:9]
	v_cndmask_b32_e64 v62, v62, 0, s[10:11]
	v_cndmask_b32_e64 v63, v63, 0, s[12:13]
	v_cndmask_b32_e64 v56, v56, 0, s[14:15]
	v_cndmask_b32_e64 v57, 0, v57, s[16:17]
	v_cndmask_b32_e64 v58, v58, 0, s[18:19]
	v_cndmask_b32_e64 v59, v59, 0, s[20:21]
	v_cvt_pk_bf16_f32 v60, v60, v61
	v_cvt_pk_bf16_f32 v61, v62, v63
	v_cvt_pk_bf16_f32 v56, v56, v57
	v_cvt_pk_bf16_f32 v57, v58, v59
	ds_write_b64 v154, v[60:61] offset:57344
	ds_write_b64 v155, v[56:57] offset:57344
	s_waitcnt lgkmcnt(0)
	s_barrier
	ds_read_b128 v[252:255], v156 offset:57344
	ds_read_b128 v[248:251], v159 offset:57344
	v_add_u32_e32 v173, v146, v135
	ds_read_b128 v[232:235], v173
	v_add_u32_e32 v176, v146, v138
	ds_read_b128 v[236:239], v176
	v_add_u32_e32 v231, v147, v135
	ds_read_b128 v[240:243], v231
	v_add_u32_e32 v173, v147, v138
	ds_read_b128 v[244:247], v173
	v_add_u32_e32 v116, s71, v145
	v_ashrrev_i32_e32 v117, 31, v116
	v_lshlrev_b32_e32 v84, 1, v82
	v_mov_b32_e32 v97, v85
	v_mov_b32_e32 v99, v85
	v_lshlrev_b64 v[228:229], 11, v[116:117]
	v_lshl_add_u64 v[228:229], s[28:29], 0, v[228:229]
	s_waitcnt lgkmcnt(5)
	v_mfma_f32_16x16x32_bf16 v[178:181], v[212:215], v[252:255], 0
	v_mfma_f32_16x16x32_bf16 v[182:185], v[216:219], v[252:255], 0
	s_waitcnt lgkmcnt(4)
	v_mfma_f32_16x16x32_bf16 v[178:181], v[220:223], v[248:251], v[178:181]
	v_mfma_f32_16x16x32_bf16 v[182:185], v[224:227], v[248:251], v[182:185]
	v_add_u32_e32 v176, v148, v135
	ds_read_b128 v[212:215], v176
	v_add_u32_e32 v231, v148, v138
	ds_read_b128 v[216:219], v231
	v_add_u32_e32 v173, v149, v135
	ds_read_b128 v[220:223], v173
	v_add_u32_e32 v176, v149, v138
	ds_read_b128 v[224:227], v176
	ds_read_b128 v[60:63], v150
	ds_read_b128 v[56:59], v151
	s_waitcnt lgkmcnt(9)
	v_mfma_f32_16x16x32_bf16 v[178:181], v[232:235], v[196:199], v[178:181]
	s_waitcnt lgkmcnt(8)
	v_mfma_f32_16x16x32_bf16 v[182:185], v[236:239], v[196:199], v[182:185]
	s_waitcnt lgkmcnt(7)
	v_mfma_f32_16x16x32_bf16 v[178:181], v[240:243], v[200:203], v[178:181]
	s_waitcnt lgkmcnt(6)
	v_mfma_f32_16x16x32_bf16 v[182:185], v[244:247], v[200:203], v[182:185]
	s_waitcnt lgkmcnt(5)
	v_mfma_f32_16x16x32_bf16 v[178:181], v[212:215], v[204:207], v[178:181]
	s_waitcnt lgkmcnt(4)
	v_mfma_f32_16x16x32_bf16 v[182:185], v[216:219], v[204:207], v[182:185]
	s_waitcnt lgkmcnt(3)
	v_mfma_f32_16x16x32_bf16 v[178:181], v[220:223], v[208:211], v[178:181]
	s_waitcnt lgkmcnt(2)
	v_mfma_f32_16x16x32_bf16 v[182:185], v[224:227], v[208:211], v[182:185]
	v_lshl_add_u64 v[174:175], v[228:229], 0, v[84:85]
	v_lshl_add_u64 v[174:175], v[174:175], 0, v[96:97]
	v_lshl_add_u64 v[228:229], v[228:229], 0, v[98:99]
	v_lshl_add_u64 v[228:229], v[228:229], 0, v[96:97]
	s_nop 4
	v_cvt_pk_bf16_f32 v186, v178, v179
	v_cvt_pk_bf16_f32 v187, v180, v181
	s_nop 0
	v_cvt_pk_bf16_f32 v188, v182, v183
	v_cvt_pk_bf16_f32 v189, v184, v185
	global_store_dwordx2 v[174:175], v[186:187], off
	global_store_dwordx2 v[228:229], v[188:189], off
	s_waitcnt lgkmcnt(0)
	s_barrier
	s_cmp_lt_u32 s72, 30
	s_cbranch_scc0 .Lgla_st1_tail
	s_waitcnt vmcnt(16)
	ds_write_b128 v120, v[0:3]
	s_waitcnt vmcnt(15)
	ds_write_b128 v120, v[4:7] offset:16384
	s_waitcnt vmcnt(14)
	ds_write_b128 v121, v[8:11] offset:32768
	s_waitcnt vmcnt(13)
	ds_write_b128 v120, v[12:15] offset:8192
	s_waitcnt vmcnt(12)
	ds_write_b128 v120, v[16:19] offset:24576
	s_waitcnt vmcnt(11)
	ds_write_b128 v121, v[20:23] offset:40960
	s_waitcnt vmcnt(10)
	ds_write_b16 v122, v24 offset:49152
	ds_write_b16_d16_hi v123, v24 offset:49280
	ds_write_b16 v124, v25 offset:49408
	ds_write_b16_d16_hi v125, v25 offset:49536
	ds_write_b16 v126, v26 offset:49664
	ds_write_b16_d16_hi v127, v26 offset:49792
	ds_write_b16 v130, v27 offset:49920
	ds_write_b16_d16_hi v131, v27 offset:50048
	s_branch .Lgla_st1_done
.Lgla_st1_tail:
	s_waitcnt vmcnt(8)
	ds_write_b128 v120, v[0:3]
	s_waitcnt vmcnt(7)
	ds_write_b128 v120, v[4:7] offset:16384
	s_waitcnt vmcnt(6)
	ds_write_b128 v121, v[8:11] offset:32768
	s_waitcnt vmcnt(5)
	ds_write_b128 v120, v[12:15] offset:8192
	s_waitcnt vmcnt(4)
	ds_write_b128 v120, v[16:19] offset:24576
	s_waitcnt vmcnt(3)
	ds_write_b128 v121, v[20:23] offset:40960
	s_waitcnt vmcnt(2)
	ds_write_b16 v122, v24 offset:49152
	ds_write_b16_d16_hi v123, v24 offset:49280
	ds_write_b16 v124, v25 offset:49408
	ds_write_b16_d16_hi v125, v25 offset:49536
	ds_write_b16 v126, v26 offset:49664
	ds_write_b16_d16_hi v127, v26 offset:49792
	ds_write_b16 v130, v27 offset:49920
	ds_write_b16_d16_hi v131, v27 offset:50048
.Lgla_st1_done:
	s_and_saveexec_b64 s[56:57], s[4:5]
	ds_write_b32 v152, v83
	s_or_b64 exec, exec, s[56:57]
	s_cmp_gt_u32 s72, 28
	s_waitcnt lgkmcnt(0)
	s_barrier
	s_cbranch_scc1 .LBB0_358
	v_add_u32_e32 v0, 0xc0, v177
	v_mad_i64_i32 v[4:5], s[56:57], v0, s73, v[86:87]
	s_ashr_i32 s31, s30, 31
	s_lshl_b64 s[56:57], s[30:31], 14
	v_lshl_add_u64 v[8:9], v[88:89], 0, s[56:57]
	v_mov_b32_e32 v81, v85
	v_lshl_add_u64 v[16:17], v[8:9], 0, v[80:81]
	v_add_u32_e32 v8, 0xe0, v177
	v_add_co_u32_e32 v20, vcc, 0x2000, v16
	v_add_u32_e32 v24, 0xc0, v95
	v_mad_i64_i32 v[18:19], s[56:57], v8, s73, v[86:87]
	v_addc_co_u32_e32 v21, vcc, 0, v17, vcc
	v_mad_i64_i32 v[24:25], s[56:57], v24, s73, v[92:93]
	global_load_dwordx4 v[0:3], v[4:5], off
	s_nop 0
	global_load_dwordx4 v[4:7], v[4:5], off offset:1024
	s_nop 0
	global_load_dwordx4 v[8:11], v[16:17], off
	global_load_dwordx4 v[12:15], v[18:19], off
	s_nop 0
	global_load_dwordx4 v[16:19], v[18:19], off offset:1024
	s_nop 0
	global_load_dwordx4 v[20:23], v[20:21], off
	v_mov_b32_e32 v83, 0
	global_load_dwordx4 v[24:27], v[24:25], off offset:2048
	v_ashrrev_i32_e32 v95, 31, v94
	v_lshlrev_b64 v[194:195], 11, v[94:95]
	v_lshl_add_u64 v[194:195], v[90:91], 0, v[194:195]
	global_load_dword v83, v[194:195], off
.LBB0_357:
.LBB0_358:
	ds_read_b128 v[248:251], v133
	v_add_u32_e32 v173, v134, v136
	ds_read_b128 v[196:199], v173
	v_add_u32_e32 v176, v137, v135
	ds_read_b128 v[212:215], v176 offset:16384
	v_add_u32_e32 v231, v137, v138
	ds_read_b128 v[216:219], v231 offset:16384
	v_add_u32_e32 v173, v134, v139
	ds_read_b128 v[200:203], v173
	v_add_u32_e32 v176, v140, v135
	ds_read_b128 v[220:223], v176 offset:16384
	v_add_u32_e32 v231, v140, v138
	ds_read_b128 v[224:227], v231 offset:16384
	v_add_u32_e32 v173, v134, v141
	ds_read_b128 v[204:207], v173
	v_add_u32_e32 v176, v142, v135
	ds_read_b128 v[232:235], v176 offset:16384
	v_add_u32_e32 v231, v142, v138
	ds_read_b128 v[236:239], v231 offset:16384
	v_add_u32_e32 v173, v134, v143
	ds_read_b128 v[208:211], v173
	v_add_u32_e32 v176, v144, v135
	ds_read_b128 v[240:243], v176 offset:16384
	v_add_u32_e32 v231, v144, v138
	ds_read_b128 v[244:247], v231 offset:16384
	v_pk_mul_f32 v[76:77], v[60:61], v[76:77]
	v_pk_mul_f32 v[78:79], v[62:63], v[78:79]
	v_pk_mul_f32 v[72:73], v[60:61], v[72:73]
	v_pk_mul_f32 v[74:75], v[62:63], v[74:75]
	v_pk_mul_f32 v[68:69], v[60:61], v[68:69]
	v_pk_mul_f32 v[70:71], v[62:63], v[70:71]
	v_pk_mul_f32 v[64:65], v[60:61], v[64:65]
	v_pk_mul_f32 v[66:67], v[62:63], v[66:67]
	v_pk_fma_f32 v[112:113], v[112:113], v[56:57], v[76:77]
	v_pk_fma_f32 v[114:115], v[114:115], v[58:59], v[78:79]
	v_pk_fma_f32 v[108:109], v[108:109], v[56:57], v[72:73]
	v_pk_fma_f32 v[110:111], v[110:111], v[58:59], v[74:75]
	v_pk_fma_f32 v[104:105], v[104:105], v[56:57], v[68:69]
	v_pk_fma_f32 v[106:107], v[106:107], v[58:59], v[70:71]
	v_pk_fma_f32 v[100:101], v[100:101], v[56:57], v[64:65]
	v_pk_fma_f32 v[102:103], v[102:103], v[58:59], v[66:67]
	s_waitcnt lgkmcnt(12)
	v_pk_mul_f32 v[64:65], v[112:113], v[248:249]
	v_pk_mul_f32 v[66:67], v[114:115], v[250:251]
	v_pk_mul_f32 v[68:69], v[108:109], v[248:249]
	v_pk_mul_f32 v[70:71], v[110:111], v[250:251]
	v_cvt_pk_bf16_f32 v72, v64, v65
	v_cvt_pk_bf16_f32 v73, v66, v67
	v_cvt_pk_bf16_f32 v74, v68, v69
	v_cvt_pk_bf16_f32 v75, v70, v71
	ds_write2st64_b64 v153, v[72:73], v[74:75] offset1:8
	v_pk_mul_f32 v[64:65], v[104:105], v[248:249]
	v_pk_mul_f32 v[66:67], v[106:107], v[250:251]
	v_pk_mul_f32 v[68:69], v[100:101], v[248:249]
	v_pk_mul_f32 v[70:71], v[102:103], v[250:251]
	v_cvt_pk_bf16_f32 v72, v64, v65
	v_cvt_pk_bf16_f32 v73, v66, v67
	v_cvt_pk_bf16_f32 v74, v68, v69
	v_cvt_pk_bf16_f32 v75, v70, v71
	ds_write2st64_b64 v153, v[72:73], v[74:75] offset0:16 offset1:24
	s_waitcnt lgkmcnt(12)
	v_mfma_f32_16x16x32_bf16 v[60:63], v[212:215], v[196:199], 0
	s_waitcnt lgkmcnt(11)
	v_mfma_f32_16x16x32_bf16 v[56:59], v[216:219], v[196:199], 0
	ds_read_b128 v[252:255], v162 offset:32768
	ds_read_b128 v[212:215], v163 offset:49152
	ds_read_b128 v[216:219], v164 offset:49152
	s_waitcnt lgkmcnt(12)
	v_mfma_f32_16x16x32_bf16 v[60:63], v[220:223], v[200:203], v[60:63]
	s_waitcnt lgkmcnt(11)
	v_mfma_f32_16x16x32_bf16 v[56:59], v[224:227], v[200:203], v[56:59]
	ds_read_b128 v[220:223], v165 offset:49152
	ds_read_b128 v[224:227], v166 offset:49152
	s_waitcnt lgkmcnt(11)
	v_mfma_f32_16x16x32_bf16 v[60:63], v[232:235], v[204:207], v[60:63]
	s_waitcnt lgkmcnt(10)
	v_mfma_f32_16x16x32_bf16 v[56:59], v[236:239], v[204:207], v[56:59]
	ds_read_b128 v[248:251], v167 offset:32768
	ds_read_b128 v[232:235], v168 offset:49152
	ds_read_b128 v[236:239], v169 offset:49152
	s_waitcnt lgkmcnt(11)
	v_mfma_f32_16x16x32_bf16 v[60:63], v[240:243], v[208:211], v[60:63]
	s_waitcnt lgkmcnt(10)
	v_mfma_f32_16x16x32_bf16 v[56:59], v[244:247], v[208:211], v[56:59]
	ds_read_b128 v[240:243], v170 offset:49152
	ds_read_b128 v[244:247], v171 offset:49152
	s_waitcnt lgkmcnt(8)
	v_mfma_f32_16x16x32_bf16 v[76:79], v[252:255], v[212:215], 0
	s_waitcnt lgkmcnt(7)
	v_mfma_f32_16x16x32_bf16 v[72:75], v[252:255], v[216:219], 0
	s_waitcnt lgkmcnt(6)
	v_mfma_f32_16x16x32_bf16 v[68:71], v[252:255], v[220:223], 0
	s_waitcnt lgkmcnt(5)
	v_mfma_f32_16x16x32_bf16 v[64:67], v[252:255], v[224:227], 0
	ds_read_b128 v[212:215], v157 offset:49152
	ds_read_b128 v[216:219], v158 offset:49152
	ds_read_b128 v[220:223], v160 offset:49152
	ds_read_b128 v[224:227], v161 offset:49152
	s_waitcnt lgkmcnt(7)
	v_mfma_f32_16x16x32_bf16 v[76:79], v[248:251], v[232:235], v[76:79]
	s_waitcnt lgkmcnt(6)
	v_mfma_f32_16x16x32_bf16 v[72:75], v[248:251], v[236:239], v[72:75]
	s_waitcnt lgkmcnt(5)
	v_mfma_f32_16x16x32_bf16 v[68:71], v[248:251], v[240:243], v[68:71]
	s_waitcnt lgkmcnt(4)
	v_mfma_f32_16x16x32_bf16 v[64:67], v[248:251], v[244:247], v[64:67]
	v_cndmask_b32_e64 v60, v60, 0, s[6:7]
	v_cndmask_b32_e64 v61, 0, v61, s[8:9]
	v_cndmask_b32_e64 v62, v62, 0, s[10:11]
	v_cndmask_b32_e64 v63, v63, 0, s[12:13]
	v_cndmask_b32_e64 v56, v56, 0, s[14:15]
	v_cndmask_b32_e64 v57, 0, v57, s[16:17]
	v_cndmask_b32_e64 v58, v58, 0, s[18:19]
	v_cndmask_b32_e64 v59, v59, 0, s[20:21]
	v_cvt_pk_bf16_f32 v60, v60, v61
	v_cvt_pk_bf16_f32 v61, v62, v63
	v_cvt_pk_bf16_f32 v56, v56, v57
	v_cvt_pk_bf16_f32 v57, v58, v59
	ds_write_b64 v154, v[60:61] offset:57344
	ds_write_b64 v155, v[56:57] offset:57344
	s_waitcnt lgkmcnt(0)
	s_barrier
	ds_read_b128 v[252:255], v156 offset:57344
	ds_read_b128 v[248:251], v159 offset:57344
	v_add_u32_e32 v173, v146, v135
	ds_read_b128 v[232:235], v173
	v_add_u32_e32 v176, v146, v138
	ds_read_b128 v[236:239], v176
	v_add_u32_e32 v231, v147, v135
	ds_read_b128 v[240:243], v231
	v_add_u32_e32 v173, v147, v138
	ds_read_b128 v[244:247], v173
	v_add_u32_e32 v228, 64, v116
	v_ashrrev_i32_e32 v229, 31, v228
	v_mov_b32_e32 v97, v85
	v_mov_b32_e32 v99, v85
	v_lshlrev_b64 v[228:229], 11, v[228:229]
	v_lshl_add_u64 v[228:229], s[28:29], 0, v[228:229]
	s_waitcnt lgkmcnt(5)
	v_mfma_f32_16x16x32_bf16 v[178:181], v[212:215], v[252:255], 0
	v_mfma_f32_16x16x32_bf16 v[182:185], v[216:219], v[252:255], 0
	s_waitcnt lgkmcnt(4)
	v_mfma_f32_16x16x32_bf16 v[178:181], v[220:223], v[248:251], v[178:181]
	v_mfma_f32_16x16x32_bf16 v[182:185], v[224:227], v[248:251], v[182:185]
	v_add_u32_e32 v176, v148, v135
	ds_read_b128 v[212:215], v176
	v_add_u32_e32 v231, v148, v138
	ds_read_b128 v[216:219], v231
	v_add_u32_e32 v173, v149, v135
	ds_read_b128 v[220:223], v173
	v_add_u32_e32 v176, v149, v138
	ds_read_b128 v[224:227], v176
	ds_read_b128 v[60:63], v150
	ds_read_b128 v[56:59], v151
	s_waitcnt lgkmcnt(9)
	v_mfma_f32_16x16x32_bf16 v[178:181], v[232:235], v[196:199], v[178:181]
	s_waitcnt lgkmcnt(8)
	v_mfma_f32_16x16x32_bf16 v[182:185], v[236:239], v[196:199], v[182:185]
	s_waitcnt lgkmcnt(7)
	v_mfma_f32_16x16x32_bf16 v[178:181], v[240:243], v[200:203], v[178:181]
	s_waitcnt lgkmcnt(6)
	v_mfma_f32_16x16x32_bf16 v[182:185], v[244:247], v[200:203], v[182:185]
	s_waitcnt lgkmcnt(5)
	v_mfma_f32_16x16x32_bf16 v[178:181], v[212:215], v[204:207], v[178:181]
	s_waitcnt lgkmcnt(4)
	v_mfma_f32_16x16x32_bf16 v[182:185], v[216:219], v[204:207], v[182:185]
	s_waitcnt lgkmcnt(3)
	v_mfma_f32_16x16x32_bf16 v[178:181], v[220:223], v[208:211], v[178:181]
	s_waitcnt lgkmcnt(2)
	v_mfma_f32_16x16x32_bf16 v[182:185], v[224:227], v[208:211], v[182:185]
	v_lshl_add_u64 v[174:175], v[228:229], 0, v[84:85]
	v_lshl_add_u64 v[174:175], v[174:175], 0, v[96:97]
	v_lshl_add_u64 v[228:229], v[228:229], 0, v[98:99]
	v_lshl_add_u64 v[228:229], v[228:229], 0, v[96:97]
	s_andn2_b64 vcc, exec, s[54:55]
	s_nop 4
	v_cvt_pk_bf16_f32 v186, v178, v179
	v_cvt_pk_bf16_f32 v187, v180, v181
	s_nop 0
	v_cvt_pk_bf16_f32 v188, v182, v183
	v_cvt_pk_bf16_f32 v189, v184, v185
	global_store_dwordx2 v[174:175], v[186:187], off
	global_store_dwordx2 v[228:229], v[188:189], off
	s_waitcnt lgkmcnt(0)
	s_barrier
	s_cbranch_vccnz .LBB0_347
	s_waitcnt vmcnt(16)
	ds_write_b128 v120, v[28:31]
	s_waitcnt vmcnt(15)
	ds_write_b128 v120, v[32:35] offset:16384
	s_waitcnt vmcnt(14)
	ds_write_b128 v121, v[40:43] offset:32768
	s_waitcnt vmcnt(13)
	ds_write_b128 v120, v[36:39] offset:8192
	s_waitcnt vmcnt(12)
	ds_write_b128 v120, v[44:47] offset:24576
	s_waitcnt vmcnt(11)
	ds_write_b128 v121, v[48:51] offset:40960
	s_waitcnt vmcnt(10)
	ds_write_b16 v122, v52 offset:49152
	ds_write_b16_d16_hi v123, v52 offset:49280
	ds_write_b16 v124, v53 offset:49408
	ds_write_b16_d16_hi v125, v53 offset:49536
	ds_write_b16 v126, v54 offset:49664
	ds_write_b16_d16_hi v127, v54 offset:49792
	ds_write_b16 v130, v55 offset:49920
	ds_write_b16_d16_hi v131, v55 offset:50048
	s_and_saveexec_b64 s[54:55], s[4:5]
	s_cbranch_execz .LBB0_346
	ds_write_b32 v152, v172
	s_branch .LBB0_346
